# vtranspose loads pipelined across items; x->bf16 row loop: 4 loads batched with one wait
# speedup vs baseline: 1.0003x; 1.0003x over previous
.LBB0_249:
	v_add_u32_e32 v2, 0xffff8000, v0
	v_cmp_gt_i32_e64 s[10:11], s33, v0
	v_cmp_lt_i32_e64 s[12:13], v20, v19
	s_nop 0
	v_cndmask_b32_e64 v11, 0, v1, s[10:11]
	v_cndmask_b32_e64 v10, v2, v0, s[10:11]
	v_cndmask_b32_e64 v2, v16, v17, s[10:11]
	s_waitcnt lgkmcnt(0)
	v_cndmask_b32_e64 v29, v12, v13, s[10:11]
	v_cndmask_b32_e64 v28, v14, v15, s[10:11]
	v_lshlrev_b64 v[30:31], 12, v[10:11]
	v_lshl_add_u64 v[32:33], s[2:3], 0, v[2:3]
	v_lshlrev_b64 v[34:35], 11, v[10:11]
	v_lshl_add_u64 v[28:29], v[28:29], 0, v[30:31]
	v_lshl_add_u64 v[32:33], v[32:33], 0, v[34:35]
	v_lshl_add_u64 v[40:41], v[28:29], 0, v[4:5]
	v_lshl_add_u64 v[44:45], v[32:33], 0, v[6:7]
	global_load_dwordx4 v[28:31], v[40:41], off
	global_load_dwordx4 v[32:35], v[40:41], off offset:1024
	global_load_dwordx4 v[36:39], v[40:41], off offset:2048
	global_load_dwordx4 v[40:43], v[40:41], off offset:3072
	s_waitcnt vmcnt(0)
	v_cvt_pk_bf16_f32 v46, v28, v29
	v_cvt_pk_bf16_f32 v47, v30, v31
	global_store_dwordx2 v[44:45], v[46:47], off
	v_cvt_pk_bf16_f32 v48, v32, v33
	v_cvt_pk_bf16_f32 v49, v34, v35
	global_store_dwordx2 v[44:45], v[48:49], off offset:512
	v_cvt_pk_bf16_f32 v50, v36, v37
	v_cvt_pk_bf16_f32 v51, v38, v39
	global_store_dwordx2 v[44:45], v[50:51], off offset:1024
	v_cndmask_b32_e64 v2, v18, v20, s[12:13]
	v_lshlrev_b32_e32 v2, 2, v2
	v_cmp_lt_i32_e64 s[12:13], v21, v19
	v_mul_f32_e32 v9, v29, v29
	v_fmac_f32_e32 v9, v28, v28
	v_fmac_f32_e32 v9, v30, v30
	v_fmac_f32_e32 v9, v31, v31
	v_mul_f32_e32 v28, v33, v33
	v_fmac_f32_e32 v28, v32, v32
	v_fmac_f32_e32 v28, v34, v34
	v_fmac_f32_e32 v28, v35, v35
	v_add_f32_e32 v9, v9, v28
	v_mul_f32_e32 v28, v37, v37
	v_fmac_f32_e32 v28, v36, v36
	v_fmac_f32_e32 v28, v38, v38
	v_fmac_f32_e32 v28, v39, v39
	v_add_f32_e32 v9, v9, v28
	s_waitcnt vmcnt(0)
	v_mul_f32_e32 v28, v41, v41
	v_fmac_f32_e32 v28, v40, v40
	v_fmac_f32_e32 v28, v42, v42
	v_fmac_f32_e32 v28, v43, v43
	v_add_f32_e32 v9, v9, v28
	ds_bpermute_b32 v2, v2, v9
	v_cndmask_b32_e64 v28, v18, v21, s[12:13]
	v_lshlrev_b32_e32 v28, 2, v28
	v_cmp_lt_i32_e64 s[12:13], v22, v19
	v_cvt_pk_bf16_f32 v30, v40, v41
	s_waitcnt lgkmcnt(0)
	v_add_f32_e32 v2, v9, v2
	ds_bpermute_b32 v9, v28, v2
	v_cndmask_b32_e64 v28, v18, v22, s[12:13]
	v_lshlrev_b32_e32 v28, 2, v28
	v_cmp_lt_i32_e64 s[12:13], v23, v19
	v_cvt_pk_bf16_f32 v31, v42, v43
	s_waitcnt lgkmcnt(0)
	v_add_f32_e32 v2, v2, v9
	ds_bpermute_b32 v9, v28, v2
	v_cndmask_b32_e64 v28, v18, v23, s[12:13]
	v_lshlrev_b32_e32 v28, 2, v28
	v_cmp_lt_i32_e64 s[12:13], v24, v19
	flat_store_dwordx2 v[44:45], v[30:31] offset:1536
	s_waitcnt lgkmcnt(0)
	v_add_f32_e32 v2, v2, v9
	ds_bpermute_b32 v9, v28, v2
	v_cndmask_b32_e64 v28, v18, v24, s[12:13]
	v_lshlrev_b32_e32 v28, 2, v28
	v_cmp_lt_i32_e64 s[12:13], v25, v19
	s_waitcnt lgkmcnt(0)
	v_add_f32_e32 v2, v2, v9
	ds_bpermute_b32 v9, v28, v2
	v_cndmask_b32_e64 v29, v18, v25, s[12:13]
	s_waitcnt lgkmcnt(0)
	v_add_f32_e32 v28, v2, v9
	v_lshlrev_b32_e32 v2, 2, v29
	ds_bpermute_b32 v29, v2, v28
	s_and_saveexec_b64 s[12:13], vcc
	s_cbranch_execz .LBB0_248
	v_cndmask_b32_e64 v2, v26, v27, s[10:11]
	v_lshl_add_u64 v[30:31], s[2:3], 0, v[2:3]
	v_lshlrev_b64 v[10:11], 6, v[10:11]
	v_lshl_add_u64 v[10:11], v[30:31], 0, v[10:11]
	v_mov_b32_e32 v9, v3
	s_waitcnt lgkmcnt(0)
	v_add_f32_e32 v2, v28, v29
	v_lshl_add_u64 v[10:11], v[10:11], 0, v[8:9]
	v_cndmask_b32_e64 v2, 0, v2, s[8:9]
	flat_store_dword v[10:11], v2
	s_branch .LBB0_248

.LBB0_1832:
	s_cmpk_gt_i32 s90, 0xbff
	s_cbranch_scc1 .LBB0_1839
	s_waitcnt lgkmcnt(0)
	v_lshlrev_b64 v[0:1], 11, v[176:177]
	s_add_u32 s8, s2, 0x1b400000
	v_and_b32_e32 v1, 0x7ff, v1
	v_and_b32_e32 v0, 0xffff8000, v0
	s_addc_u32 s9, s3, 0
	s_movk_i32 s10, 0x110
	v_lshl_add_u64 v[0:1], s[2:3], 0, v[0:1]
	s_mov_b64 s[2:3], 0x18400000
	v_and_b32_e32 v6, 3, v176
	v_lshrrev_b32_e32 v7, 2, v170
	v_add_u32_e32 v8, 0xfffffe00, v176
	v_lshlrev_b32_e32 v9, 3, v176
	v_lshlrev_b32_e32 v10, 1, v151
	v_mul_lo_u32 v11, v171, s10
	v_lshl_add_u64 v[0:1], v[0:1], 0, s[2:3]
	s_movk_i32 s11, 0x600
	v_mov_b32_e32 v3, 0
	s_mov_b64 s[2:3], 0x100000
	s_mov_b32 s12, s90
	v_and_b32_e32 v42, 56, v9
	v_lshlrev_b32_e32 v46, 1, v42
	v_mov_b32_e32 v47, 0
	v_mad_u32_u24 v44, v42, s10, v10
	s_mov_b64 s[30:31], 0x18000
	s_mul_hi_i32 s22, s12, 0x2aaaaaab
	s_lshr_b32 s23, s22, 31
	s_ashr_i32 s24, s22, 1
	s_add_i32 s24, s24, s23
	s_mul_i32 s25, s24, 12
	s_sub_i32 s25, s12, s25
	s_lshl_b32 s24, s24, 7
	s_lshl_b32 s26, s25, 6
	s_ashr_i32 s27, s26, 31
	s_lshl_b64 s[26:27], s[26:27], 1
	s_add_u32 s26, s8, s26
	s_addc_u32 s27, s9, s27
	v_add_u32_e32 v38, s24, v151
	v_mov_b32_e32 v40, s26
	v_mov_b32_e32 v41, s27
	v_mad_i64_i32 v[38:39], s[28:29], v38, s11, v[40:41]
	v_lshl_add_u64 v[38:39], v[38:39], 0, v[46:47]
	global_load_dwordx4 v[30:33], v[38:39], off
	v_lshl_add_u64 v[38:39], v[38:39], 0, s[30:31]
	global_load_dwordx4 v[34:37], v[38:39], off
	s_waitcnt vmcnt(0)
	s_branch .Lvt_afterwait
.LBB0_1834:
	s_waitcnt vmcnt(2)
.Lvt_afterwait:
	s_mul_hi_i32 s6, s12, 0x2aaaaaab
	s_lshr_b32 s7, s6, 31
	s_ashr_i32 s4, s6, 1
	s_add_i32 s4, s4, s7
	s_mul_i32 s5, s4, 12
	s_sub_i32 s13, s12, s5
	s_lshl_b32 s14, s4, 7
	s_lshl_b32 s4, s13, 6
	s_ashr_i32 s5, s4, 31
	s_lshl_b64 s[4:5], s[4:5], 1
	s_add_u32 s16, s8, s4
	s_addc_u32 s17, s9, s5
	s_barrier
	ds_write_b16 v44, v30
	ds_write_b16_d16_hi v44, v30 offset:272
	ds_write_b16 v44, v31 offset:544
	ds_write_b16_d16_hi v44, v31 offset:816
	ds_write_b16 v44, v32 offset:1088
	ds_write_b16_d16_hi v44, v32 offset:1360
	ds_write_b16 v44, v33 offset:1632
	ds_write_b16_d16_hi v44, v33 offset:1904
	ds_write_b16 v44, v34 offset:128
	ds_write_b16_d16_hi v44, v34 offset:400
	ds_write_b16 v44, v35 offset:672
	ds_write_b16_d16_hi v44, v35 offset:944
	ds_write_b16 v44, v36 offset:1216
	ds_write_b16_d16_hi v44, v36 offset:1488
	ds_write_b16 v44, v37 offset:1760
	ds_write_b16_d16_hi v44, v37 offset:2032
	s_add_i32 s21, s12, s33
	s_cmpk_gt_i32 s21, 0xbff
	s_cbranch_scc1 .Lvt_nonext
	s_mul_hi_i32 s22, s21, 0x2aaaaaab
	s_lshr_b32 s23, s22, 31
	s_ashr_i32 s24, s22, 1
	s_add_i32 s24, s24, s23
	s_mul_i32 s25, s24, 12
	s_sub_i32 s25, s21, s25
	s_lshl_b32 s24, s24, 7
	s_lshl_b32 s26, s25, 6
	s_ashr_i32 s27, s26, 31
	s_lshl_b64 s[26:27], s[26:27], 1
	s_add_u32 s26, s8, s26
	s_addc_u32 s27, s9, s27
	v_add_u32_e32 v38, s24, v151
	v_mov_b32_e32 v40, s26
	v_mov_b32_e32 v41, s27
	v_mad_i64_i32 v[38:39], s[28:29], v38, s11, v[40:41]
	v_lshl_add_u64 v[38:39], v[38:39], 0, v[46:47]
	global_load_dwordx4 v[30:33], v[38:39], off
	v_lshl_add_u64 v[38:39], v[38:39], 0, s[30:31]
	global_load_dwordx4 v[34:37], v[38:39], off
.Lvt_nonext:
	s_ashr_i32 s5, s13, 2
	s_lshl_b32 s16, s5, 1
	s_lshl_b32 s15, 1, s16
	v_cvt_f32_u32_e32 v2, s15
	s_ashr_i32 s4, s6, 8
	s_add_i32 s4, s4, s7
	s_lshl_b32 s6, s4, 14
	v_rcp_iflag_f32_e32 v2, v2
	s_sub_i32 s14, s14, s6
	s_cmp_lt_u32 s13, 4
	s_cselect_b64 vcc, -1, 0
	v_mul_f32_e32 v2, 0x4f7ffffe, v2
	v_cvt_u32_f32_e32 v2, v2
	s_cmp_eq_u32 s5, 1
	s_cselect_b64 s[6:7], -1, 0
	s_sub_i32 s18, 0, s15
	v_readfirstlane_b32 s19, v2
	s_ashr_i32 s17, s14, 31
	s_mul_i32 s18, s18, s19
	s_add_i32 s14, s14, s17
	s_mul_hi_u32 s18, s19, s18
	s_xor_b32 s14, s14, s17
	s_add_i32 s19, s19, s18
	s_mul_i32 s4, s4, 12
	s_mul_hi_u32 s18, s14, s19
	s_add_i32 s4, s4, s13
	s_mul_i32 s19, s18, s15
	s_ashr_i32 s5, s4, 31
	s_sub_i32 s14, s14, s19
	s_lshl_b64 s[4:5], s[4:5], 21
	s_lshr_b32 s13, 0x4000, s16
	s_sub_i32 s19, s14, s15
	s_add_i32 s20, s18, 1
	s_cmp_ge_u32 s14, s15
	s_cselect_b32 s18, s20, s18
	v_cndmask_b32_e64 v4, 0, v6, s[6:7]
	s_cselect_b32 s14, s19, s14
	s_add_i32 s19, s18, 1
	v_cndmask_b32_e32 v4, v4, v170, vcc
	s_cmp_ge_u32 s14, s15
	v_lshlrev_b32_e32 v5, 3, v4
	s_cselect_b32 s14, s19, s18
	v_or_b32_e32 v13, 1, v5
	s_xor_b32 s14, s14, s17
	v_lshlrev_b32_e32 v19, s16, v13
	v_or_b32_e32 v13, 2, v5
	s_sub_i32 s14, s14, s17
	v_lshlrev_b32_e32 v18, s16, v13
	v_or_b32_e32 v13, 3, v5
	s_ashr_i32 s15, s14, 31
	v_lshlrev_b32_e32 v17, s16, v13
	v_or_b32_e32 v13, 4, v5
	v_cndmask_b32_e64 v2, v170, v7, s[6:7]
	v_lshlrev_b32_e32 v16, s16, v13
	v_or_b32_e32 v13, 5, v5
	s_lshl_b64 s[6:7], s[14:15], 1
	v_cndmask_b32_e64 v2, v2, 0, vcc
	v_lshlrev_b32_e32 v15, s16, v13
	v_or_b32_e32 v13, 6, v5
	s_add_u32 s4, s6, s4
	v_lshlrev_b32_e32 v12, s16, v5
	v_lshlrev_b32_e32 v14, s16, v13
	v_or_b32_e32 v5, 7, v5
	v_mul_u32_u24_e32 v21, s13, v2
	v_lshl_add_u32 v13, v2, 1, v11
	v_lshlrev_b32_e32 v2, 4, v4
	s_addc_u32 s5, s7, s5
	v_lshlrev_b32_e32 v20, s16, v5
	v_lshl_add_u64 v[4:5], s[4:5], 0, v[2:3]
	v_lshlrev_b32_e32 v2, 1, v21
	v_lshl_add_u64 v[4:5], v[4:5], 0, v[2:3]
	v_lshlrev_b32_e32 v12, 1, v12
	v_lshl_add_u64 v[4:5], v[0:1], 0, v[4:5]
	v_lshlrev_b32_e32 v2, 1, v20
	v_lshlrev_b32_e32 v14, 1, v14
	v_lshlrev_b32_e32 v15, 1, v15
	v_lshlrev_b32_e32 v16, 1, v16
	v_lshlrev_b32_e32 v17, 1, v17
	v_lshlrev_b32_e32 v18, 1, v18
	v_lshlrev_b32_e32 v19, 1, v19
	s_mov_b64 s[4:5], 0
	v_mov_b32_e32 v20, v8
	s_waitcnt lgkmcnt(0)
	s_barrier
.LBB0_1837:
	v_add_u32_e32 v21, v13, v12
	v_add_u32_e32 v22, v13, v19
	v_add_u32_e32 v23, v13, v18
	v_add_u32_e32 v24, v13, v17
	v_add_u32_e32 v25, v13, v16
	v_add_u32_e32 v26, v13, v15
	v_add_u32_e32 v27, v13, v14
	v_add_u32_e32 v28, v13, v2
	ds_read_u16 v21, v21
	ds_read_u16 v22, v22
	ds_read_u16 v23, v23
	ds_read_u16 v24, v24
	ds_read_u16 v25, v25
	ds_read_u16 v26, v26
	ds_read_u16 v27, v27
	ds_read_u16 v28, v28
	v_add_co_u32_e32 v20, vcc, 0x200, v20
	s_xor_b64 s[6:7], vcc, -1
	s_and_b64 s[6:7], exec, s[6:7]
	s_waitcnt lgkmcnt(0)
	v_lshl_or_b32 v22, v22, 16, v21
	s_waitcnt lgkmcnt(4)
	v_lshl_or_b32 v23, v24, 16, v23
	s_waitcnt lgkmcnt(2)
	v_lshl_or_b32 v24, v26, 16, v25
	s_waitcnt lgkmcnt(0)
	v_lshl_or_b32 v25, v28, 16, v27
	v_add_u32_e32 v13, 0x2200, v13
	s_or_b64 s[4:5], s[6:7], s[4:5]
	global_store_dwordx4 v[4:5], v[22:25], off
	v_lshl_add_u64 v[4:5], v[4:5], 0, s[2:3]
	s_andn2_b64 exec, exec, s[4:5]
	s_cbranch_execnz .LBB0_1837
	s_or_b64 exec, exec, s[4:5]
	s_add_i32 s12, s12, s33
	s_cmpk_gt_i32 s12, 0xbff
	s_cbranch_scc0 .LBB0_1834
